# phase-12 SwiGLU epilogue: all 64 packed scale multiplies per wave removed (constant dequant scales folded into exp argument and sigmoid denominator; converts in place, rest of the epilogue register-re
# speedup vs baseline: 1.0060x; 1.0000x over previous
; __device__ __forceinline__ u32x4 pack8bf(const f32x4 a, const f32x4 b) { u32x4 w; w.x = cvt_pk_bf16(a[0], a[1]); w.y = cvt_pk_bf16(a[2], a[3]); w.z = cvt_pk_bf16(b[0], b[1]); w.w = cvt_pk_bf16(b[2], b[3]); return w; }
;     __device__ __forceinline__ float qscale(const Unit& u) const { return ((u.pn >= 8 && u.pn <= 11) || u.pn == 17) ? 0.5f : 1.0f; }
; __device__ __forceinline__ void ln_stats(const float* st, int row, float& mu, float& rs) { const f32x2 s = *(const f32x2*)(st + 2 * (size_t)row); mu = s[0] * (1.0f / DM); rs = 1.0f / sqrtf(s[1] * (1.0f / DM) - mu * mu + LN_EPS); }
;     ...
;         if constexpr (QM == 2) { const float qs0_ = g.qs * E.qscale(cur), qs1_ = qs0_ * g.qs_b1; _Pragma("unroll") for (int a = 0; a < 2; ++a) _Pragma("unroll") for (int b = 0; b < 2; ++b) _Pragma("unroll") for (int m = 0; m < 4; ++m) _Pragma("unroll") for (int n = 0; n < 2; ++n) { const v4i t_ = __builtin_bit_cast(v4i, acc[a][b][m][n]); acc[a][b][m][n] = (f32x4){(float)t_[0], (float)t_[1], (float)t_[2], (float)t_[3]} * (b == 0 ? qs0_ : qs1_); } }
;     __device__ __forceinline__ void operator()(EPI_ARGS) const {
;     ...
; #pragma unroll
;         for (int ai = 0; ai < 2; ++ai)
; #pragma unroll
;             for (int m = 0; m < 4; ++m) { const int row = row0 + ai * HALF + m * 16; f32x4 r[2];
;                 float mu = 0.f, rs = 1.f; if constexpr (FOLD) ln_stats(st, row, mu, rs);
; #pragma unroll
;                 for (int n = 0; n < 2; ++n) { f32x4 g = acc[ai][0][m][n], up = acc[ai][1][m][n];
;                     if constexpr (!PRE) { g = g * ascale; up = up * ascale; }
;                     if constexpr (FOLD) { g = (g - cg[n] * mu) * rs + dg[n]; up = (up - cu[n] * mu) * rs + du[n]; }
;                     if constexpr (!PRE) up = up * oscale;
; #pragma unroll
;                     for (int j = 0; j < 4; ++j) { const float e = __builtin_amdgcn_exp2f(g[j] * -1.4426950408889634f); r[n][j] = g[j] * __builtin_amdgcn_rcpf(1.0f + e) * up[j]; } }
;                 if constexpr (F8OUT) *(u32x2*)((unsigned char*)O + (size_t)row * ldc + col0) = pack8fp8(r[0], r[1]);
;                 else *(u32x4*)((bf16_t*)O + (size_t)row * ldc + col0) = pack8bf(r[0], r[1]); }
.LBB0_4741:
	v_cvt_f32_i32_e32 v121, v121
	v_cvt_f32_i32_e32 v123, v123
	v_cvt_f32_i32_e32 v122, v122
	v_cvt_f32_i32_e32 v120, v120
	v_cvt_f32_i32_e32 v125, v125
	v_cvt_f32_i32_e32 v124, v124
	v_cvt_f32_i32_e32 v113, v113
	v_cvt_f32_i32_e32 v115, v115
	v_cvt_f32_i32_e32 v114, v114
	v_cvt_f32_i32_e32 v112, v112
	v_cvt_f32_i32_e32 v127, v127
	v_cvt_f32_i32_e32 v126, v126
	v_cvt_f32_i32_e32 v117, v117
	v_cvt_f32_i32_e32 v116, v116
	v_cvt_f32_i32_e32 v105, v105
	v_cvt_f32_i32_e32 v107, v107
	v_cvt_f32_i32_e32 v106, v106
	v_cvt_f32_i32_e32 v104, v104
	v_cvt_f32_i32_e32 v119, v119
	v_cvt_f32_i32_e32 v118, v118
	v_cvt_f32_i32_e32 v109, v109
	v_cvt_f32_i32_e32 v108, v108
	v_cvt_f32_i32_e32 v97, v97
	v_cvt_f32_i32_e32 v99, v99
	v_cvt_f32_i32_e32 v98, v98
	v_cvt_f32_i32_e32 v96, v96
	v_cvt_f32_i32_e32 v93, v93
	v_cvt_f32_i32_e32 v92, v92
	v_cvt_f32_i32_e32 v91, v91
	v_cvt_f32_i32_e32 v90, v90
	v_cvt_f32_i32_e32 v85, v85
	v_cvt_f32_i32_e32 v84, v84
	v_cvt_f32_i32_e32 v83, v83
	v_cvt_f32_i32_e32 v82, v82
	v_cvt_f32_i32_e32 v77, v77
	v_cvt_f32_i32_e32 v76, v76
	v_cvt_f32_i32_e32 v75, v75
	v_cvt_f32_i32_e32 v74, v74
	v_cvt_f32_i32_e32 v111, v111
	v_cvt_f32_i32_e32 v110, v110
	v_cvt_f32_i32_e32 v101, v101
	v_cvt_f32_i32_e32 v100, v100
	v_cvt_f32_i32_e32 v95, v95
	v_cvt_f32_i32_e32 v94, v94
	v_cvt_f32_i32_e32 v89, v89
	v_cvt_f32_i32_e32 v88, v88
	v_cvt_f32_i32_e32 v87, v87
	v_cvt_f32_i32_e32 v86, v86
	v_cvt_f32_i32_e32 v81, v81
	v_cvt_f32_i32_e32 v80, v80
	v_cvt_f32_i32_e32 v79, v79
	v_cvt_f32_i32_e32 v78, v78
	v_cvt_f32_i32_e32 v73, v73
	v_cvt_f32_i32_e32 v72, v72
	v_cvt_f32_i32_e32 v65, v65
	v_cvt_f32_i32_e32 v67, v67
	v_cvt_f32_i32_e32 v66, v66
	v_cvt_f32_i32_e32 v64, v64
	v_cvt_f32_i32_e32 v103, v103
	v_cvt_f32_i32_e32 v102, v102
	v_cvt_f32_i32_e32 v69, v69
	v_cvt_f32_i32_e32 v68, v68
	v_cvt_f32_i32_e32 v57, v57
	v_cvt_f32_i32_e32 v59, v59
	v_cvt_f32_i32_e32 v58, v58
	v_cvt_f32_i32_e32 v56, v56
	v_cvt_f32_i32_e32 v71, v71
	v_cvt_f32_i32_e32 v70, v70
	v_cvt_f32_i32_e32 v61, v61
	v_cvt_f32_i32_e32 v60, v60
	v_cvt_f32_i32_e32 v49, v49
	v_cvt_f32_i32_e32 v51, v51
	v_cvt_f32_i32_e32 v50, v50
	v_cvt_f32_i32_e32 v48, v48
	v_cvt_f32_i32_e32 v63, v63
	v_cvt_f32_i32_e32 v62, v62
	v_cvt_f32_i32_e32 v53, v53
	v_cvt_f32_i32_e32 v52, v52
	v_cvt_f32_i32_e32 v41, v41
	v_cvt_f32_i32_e32 v43, v43
	v_cvt_f32_i32_e32 v42, v42
	v_cvt_f32_i32_e32 v40, v40
	v_cvt_f32_i32_e32 v55, v55
	v_cvt_f32_i32_e32 v54, v54
	v_cvt_f32_i32_e32 v45, v45
	v_cvt_f32_i32_e32 v44, v44
	v_cvt_f32_i32_e32 v33, v33
	v_cvt_f32_i32_e32 v35, v35
	v_cvt_f32_i32_e32 v34, v34
	v_cvt_f32_i32_e32 v32, v32
	v_cvt_f32_i32_e32 v29, v29
	v_cvt_f32_i32_e32 v28, v28
	v_cvt_f32_i32_e32 v27, v27
	v_cvt_f32_i32_e32 v26, v26
	v_cvt_f32_i32_e32 v21, v21
	v_cvt_f32_i32_e32 v20, v20
	v_cvt_f32_i32_e32 v19, v19
	v_cvt_f32_i32_e32 v18, v18
	v_cvt_f32_i32_e32 v13, v13
	v_cvt_f32_i32_e32 v12, v12
	v_cvt_f32_i32_e32 v9, v9
	v_cvt_f32_i32_e32 v8, v8
	v_cvt_f32_i32_e32 v5, v5
	v_cvt_f32_i32_e32 v4, v4
	v_cvt_f32_i32_e32 v1, v1
	v_cvt_f32_i32_e32 v0, v0
	v_cvt_f32_i32_e32 v47, v47
	v_cvt_f32_i32_e32 v46, v46
	v_cvt_f32_i32_e32 v37, v37
	v_cvt_f32_i32_e32 v36, v36
	v_cvt_f32_i32_e32 v31, v31
	v_cvt_f32_i32_e32 v30, v30
	v_cvt_f32_i32_e32 v25, v25
	v_cvt_f32_i32_e32 v24, v24
	v_cvt_f32_i32_e32 v23, v23
	v_cvt_f32_i32_e32 v22, v22
	v_cvt_f32_i32_e32 v17, v17
	v_cvt_f32_i32_e32 v16, v16
	v_cvt_f32_i32_e32 v15, v15
	v_cvt_f32_i32_e32 v14, v14
	v_mul_f32_e32 v146, 0xb7afc6c0, v124
	v_exp_f32_e32 v147, v146
	v_mul_f32_e32 v146, 0xb7afc6c0, v125
	v_cvt_f32_i32_e32 v39, v39
	v_cvt_f32_i32_e32 v38, v38
	v_exp_f32_e32 v144, v146
	v_fma_f32 v147, v147, s32, s32
	v_rcp_f32_e32 v145, v147
	v_fma_f32 v147, v144, s32, s32
	v_rcp_f32_e32 v144, v147
	v_mul_f32_e32 v145, v124, v145
	v_mul_f32_e32 v124, 0xb7afc6c0, v126
	v_exp_f32_e32 v124, v124
	v_mul_f32_e32 v144, v125, v144
	v_mul_f32_e32 v125, 0xb7afc6c0, v127
	v_exp_f32_e32 v125, v125
	v_mul_f32_e32 v145, v92, v145
	v_fma_f32 v124, v124, s32, s32
	v_mul_f32_e32 v92, 0xb7afc6c0, v120
	v_rcp_f32_e32 v124, v124
	v_fma_f32 v125, v125, s32, s32
	v_exp_f32_e32 v92, v92
	v_rcp_f32_e32 v125, v125
	v_mul_f32_e32 v126, v126, v124
	v_mul_f32_e32 v144, v93, v144
	v_fma_f32 v124, v92, s32, s32
	v_mul_f32_e32 v127, v127, v125
	v_rcp_f32_e32 v124, v124
	v_mul_f32_e32 v125, 0xb7afc6c0, v121
	v_exp_f32_e32 v125, v125
	v_med3_f32 v145, v145, s63, v154
	v_mul_f32_e32 v120, v120, v124
	v_mul_f32_e32 v88, v88, v120
	v_fma_f32 v120, v125, s32, s32
	v_mul_f32_e32 v124, 0xb7afc6c0, v122
	v_rcp_f32_e32 v120, v120
	v_exp_f32_e32 v124, v124
	v_mul_f32_e32 v125, 0xb7afc6c0, v123
	v_exp_f32_e32 v125, v125
	v_mul_f32_e32 v120, v121, v120
	v_fma_f32 v121, v124, s32, s32
	v_rcp_f32_e32 v121, v121
	v_fma_f32 v124, v125, s32, s32
	v_rcp_f32_e32 v124, v124
	v_med3_f32 v144, v144, s63, v154
	v_mul_f32_e32 v122, v122, v121
	v_mul_f32_e32 v122, v90, v122
	v_mul_f32_e32 v90, v123, v124
	v_mul_f32_e32 v123, v91, v90
	v_cvt_pk_fp8_f32 v90, v145, v144
	v_mul_f32_e32 v89, v89, v120
	v_mul_f32_e32 v126, v94, v126
	v_mul_f32_e32 v127, v95, v127
	v_med3_f32 v88, v88, s63, v154
	v_med3_f32 v89, v89, s63, v154
	v_med3_f32 v144, v126, s63, v154
	v_med3_f32 v145, v127, s63, v154
	v_cvt_pk_fp8_f32 v91, v88, v89
	v_cvt_pk_fp8_f32 v90, v144, v145 op_sel:[0,0,1]
	v_med3_f32 v144, v122, s63, v154
	v_mul_f32_e32 v122, 0xb7afc6c0, v116
	v_med3_f32 v145, v123, s63, v154
	v_exp_f32_e32 v122, v122
	v_mul_f32_e32 v123, 0xb7afc6c0, v117
	v_exp_f32_e32 v123, v123
	v_cvt_pk_fp8_f32 v91, v144, v145 op_sel:[0,0,1]
	v_lshl_add_u32 v156, s44, 8, v148
	v_lshl_or_b32 v146, s42, 7, v150
	v_mov_b64_e32 v[144:145], s[16:17]
	v_ashrrev_i32_e32 v147, 31, v146
; __device__ __forceinline__ u32x4 pack8bf(const f32x4 a, const f32x4 b) { u32x4 w; w.x = cvt_pk_bf16(a[0], a[1]); w.y = cvt_pk_bf16(a[2], a[3]); w.z = cvt_pk_bf16(b[0], b[1]); w.w = cvt_pk_bf16(b[2], b[3]); return w; }
; __device__ __forceinline__ void ln_stats(const float* st, int row, float& mu, float& rs) { const f32x2 s = *(const f32x2*)(st + 2 * (size_t)row); mu = s[0] * (1.0f / DM); rs = 1.0f / sqrtf(s[1] * (1.0f / DM) - mu * mu + LN_EPS); }
;     __device__ __forceinline__ void operator()(EPI_ARGS) const {
;     ...
; #pragma unroll
;         for (int ai = 0; ai < 2; ++ai)
; #pragma unroll
;             for (int m = 0; m < 4; ++m) { const int row = row0 + ai * HALF + m * 16; f32x4 r[2];
;                 float mu = 0.f, rs = 1.f; if constexpr (FOLD) ln_stats(st, row, mu, rs);
; #pragma unroll
;                 for (int n = 0; n < 2; ++n) { f32x4 g = acc[ai][0][m][n], up = acc[ai][1][m][n];
;                     if constexpr (!PRE) { g = g * ascale; up = up * ascale; }
;                     if constexpr (FOLD) { g = (g - cg[n] * mu) * rs + dg[n]; up = (up - cu[n] * mu) * rs + du[n]; }
;                     if constexpr (!PRE) up = up * oscale;
; #pragma unroll
;                     for (int j = 0; j < 4; ++j) { const float e = __builtin_amdgcn_exp2f(g[j] * -1.4426950408889634f); r[n][j] = g[j] * __builtin_amdgcn_rcpf(1.0f + e) * up[j]; } }
;                 if constexpr (F8OUT) *(u32x2*)((unsigned char*)O + (size_t)row * ldc + col0) = pack8fp8(r[0], r[1]);
;                 else *(u32x4*)((bf16_t*)O + (size_t)row * ldc + col0) = pack8bf(r[0], r[1]); }
	v_mad_i64_i32 v[88:89], s[4:5], v156, s64, v[144:145]
	v_fma_f32 v122, v122, s32, s32
	v_lshl_add_u64 v[88:89], v[88:89], 0, v[146:147]
	v_rcp_f32_e32 v122, v122
	v_fma_f32 v123, v123, s32, s32
	v_rcp_f32_e32 v123, v123
	global_store_dwordx2 v[88:89], v[90:91], off
	v_mul_f32_e32 v91, 0xb7afc6c0, v118
	v_exp_f32_e32 v91, v91
	v_mul_f32_e32 v88, 0xb7afc6c0, v119
	v_exp_f32_e32 v88, v88
	v_mul_f32_e32 v90, v116, v122
	v_mul_f32_e32 v84, v84, v90
	v_mul_f32_e32 v90, v117, v123
	v_mul_f32_e32 v85, v85, v90
	v_fma_f32 v90, v91, s32, s32
	v_rcp_f32_e32 v90, v90
	v_fma_f32 v91, v88, s32, s32
	v_mul_f32_e32 v88, 0xb7afc6c0, v112
	v_rcp_f32_e32 v91, v91
	v_exp_f32_e32 v88, v88
	v_mul_f32_e32 v90, v118, v90
	v_mul_f32_e32 v86, v86, v90
	v_mul_f32_e32 v90, v119, v91
	v_fma_f32 v91, v88, s32, s32
	v_rcp_f32_e32 v91, v91
	v_mul_f32_e32 v88, 0xb7afc6c0, v113
	v_exp_f32_e32 v88, v88
	v_mul_f32_e32 v87, v87, v90
	v_mul_f32_e32 v90, v112, v91
	v_mul_f32_e32 v91, 0xb7afc6c0, v114
	v_mul_f32_e32 v80, v80, v90
	v_fma_f32 v90, v88, s32, s32
	v_exp_f32_e32 v91, v91
	v_mul_f32_e32 v88, 0xb7afc6c0, v115
	v_exp_f32_e32 v88, v88
	v_rcp_f32_e32 v90, v90
	v_fma_f32 v91, v91, s32, s32
	v_rcp_f32_e32 v91, v91
	v_fma_f32 v88, v88, s32, s32
	v_rcp_f32_e32 v88, v88
	v_mul_f32_e32 v90, v113, v90
	v_mul_f32_e32 v81, v81, v90
	v_mul_f32_e32 v90, v114, v91
	v_mul_f32_e32 v90, v82, v90
	v_mul_f32_e32 v82, v115, v88
	v_mul_f32_e32 v91, v83, v82
	v_med3_f32 v83, v84, s63, v154
	v_med3_f32 v84, v85, s63, v154
	v_cvt_pk_fp8_f32 v82, v83, v84
	v_med3_f32 v80, v80, s63, v154
	v_med3_f32 v81, v81, s63, v154
	v_med3_f32 v86, v86, s63, v154
	v_med3_f32 v87, v87, s63, v154
	v_cvt_pk_fp8_f32 v83, v80, v81
	v_cvt_pk_fp8_f32 v82, v86, v87 op_sel:[0,0,1]
	v_mul_f32_e32 v86, 0xb7afc6c0, v108
	v_exp_f32_e32 v86, v86
	v_mul_f32_e32 v87, 0xb7afc6c0, v109
	v_med3_f32 v80, v90, s63, v154
	v_med3_f32 v81, v91, s63, v154
	v_exp_f32_e32 v87, v87
	v_cvt_pk_fp8_f32 v83, v80, v81 op_sel:[0,0,1]
	v_or_b32_e32 v88, 16, v156
	v_mad_i64_i32 v[80:81], s[4:5], v88, s64, v[144:145]
	v_fma_f32 v86, v86, s32, s32
	v_lshl_add_u64 v[80:81], v[80:81], 0, v[146:147]
	v_rcp_f32_e32 v86, v86
	v_fma_f32 v87, v87, s32, s32
	v_rcp_f32_e32 v87, v87
	global_store_dwordx2 v[80:81], v[82:83], off
	v_mul_f32_e32 v83, 0xb7afc6c0, v110
	v_exp_f32_e32 v83, v83
	v_mul_f32_e32 v80, 0xb7afc6c0, v111
	v_exp_f32_e32 v80, v80
	v_mul_f32_e32 v82, v108, v86
	v_mul_f32_e32 v76, v76, v82
	v_mul_f32_e32 v82, v109, v87
	v_mul_f32_e32 v77, v77, v82
	v_fma_f32 v82, v83, s32, s32
	v_rcp_f32_e32 v82, v82
	v_fma_f32 v83, v80, s32, s32
	v_mul_f32_e32 v80, 0xb7afc6c0, v104
	v_rcp_f32_e32 v83, v83
	v_exp_f32_e32 v80, v80
	v_mul_f32_e32 v82, v110, v82
	v_mul_f32_e32 v78, v78, v82
	v_mul_f32_e32 v82, v111, v83
	v_fma_f32 v83, v80, s32, s32
	v_rcp_f32_e32 v83, v83
	v_mul_f32_e32 v80, 0xb7afc6c0, v105
	v_exp_f32_e32 v80, v80
	v_mul_f32_e32 v79, v79, v82
	v_mul_f32_e32 v82, v104, v83
	v_mul_f32_e32 v83, 0xb7afc6c0, v106
	v_mul_f32_e32 v72, v72, v82
	v_fma_f32 v82, v80, s32, s32
	v_exp_f32_e32 v83, v83
	v_mul_f32_e32 v80, 0xb7afc6c0, v107
	v_exp_f32_e32 v80, v80
	v_rcp_f32_e32 v82, v82
	v_fma_f32 v83, v83, s32, s32
	v_rcp_f32_e32 v83, v83
	v_fma_f32 v80, v80, s32, s32
	v_rcp_f32_e32 v80, v80
	v_mul_f32_e32 v82, v105, v82
	v_mul_f32_e32 v73, v73, v82
	v_mul_f32_e32 v82, v106, v83
	v_mul_f32_e32 v82, v74, v82
	v_mul_f32_e32 v74, v107, v80
	v_mul_f32_e32 v83, v75, v74
	v_med3_f32 v75, v76, s63, v154
	v_med3_f32 v76, v77, s63, v154
	v_cvt_pk_fp8_f32 v74, v75, v76
	v_med3_f32 v72, v72, s63, v154
	v_med3_f32 v73, v73, s63, v154
	v_med3_f32 v78, v78, s63, v154
	v_med3_f32 v79, v79, s63, v154
	v_cvt_pk_fp8_f32 v75, v72, v73
	v_cvt_pk_fp8_f32 v74, v78, v79 op_sel:[0,0,1]
	v_mul_f32_e32 v78, 0xb7afc6c0, v100
	v_exp_f32_e32 v78, v78
	v_mul_f32_e32 v79, 0xb7afc6c0, v101
	v_med3_f32 v72, v82, s63, v154
	v_med3_f32 v73, v83, s63, v154
	v_exp_f32_e32 v79, v79
	v_cvt_pk_fp8_f32 v75, v72, v73 op_sel:[0,0,1]
	v_or_b32_e32 v80, 32, v156
	v_mad_i64_i32 v[72:73], s[4:5], v80, s64, v[144:145]
	v_fma_f32 v78, v78, s32, s32
	v_lshl_add_u64 v[72:73], v[72:73], 0, v[146:147]
	v_rcp_f32_e32 v78, v78
	v_fma_f32 v79, v79, s32, s32
	v_rcp_f32_e32 v79, v79
	global_store_dwordx2 v[72:73], v[74:75], off
	v_mul_f32_e32 v75, 0xb7afc6c0, v102
	v_exp_f32_e32 v75, v75
	v_mul_f32_e32 v72, 0xb7afc6c0, v103
	v_exp_f32_e32 v72, v72
	v_mul_f32_e32 v74, v100, v78
	v_mul_f32_e32 v68, v68, v74
	v_mul_f32_e32 v74, v101, v79
	v_mul_f32_e32 v69, v69, v74
	v_fma_f32 v74, v75, s32, s32
	v_rcp_f32_e32 v74, v74
	v_fma_f32 v75, v72, s32, s32
	v_mul_f32_e32 v72, 0xb7afc6c0, v96
	v_rcp_f32_e32 v75, v75
	v_exp_f32_e32 v72, v72
	v_mul_f32_e32 v74, v102, v74
	v_mul_f32_e32 v70, v70, v74
	v_mul_f32_e32 v74, v103, v75
	v_fma_f32 v75, v72, s32, s32
	v_rcp_f32_e32 v75, v75
	v_mul_f32_e32 v72, 0xb7afc6c0, v97
	v_exp_f32_e32 v72, v72
	v_mul_f32_e32 v71, v71, v74
	v_mul_f32_e32 v74, v96, v75
	v_mul_f32_e32 v75, 0xb7afc6c0, v98
	v_mul_f32_e32 v64, v64, v74
	v_fma_f32 v74, v72, s32, s32
	v_exp_f32_e32 v75, v75
	v_mul_f32_e32 v72, 0xb7afc6c0, v99
	v_exp_f32_e32 v72, v72
	v_rcp_f32_e32 v74, v74
	v_fma_f32 v75, v75, s32, s32
	v_rcp_f32_e32 v75, v75
	v_fma_f32 v72, v72, s32, s32
	v_rcp_f32_e32 v72, v72
	v_mul_f32_e32 v74, v97, v74
	v_mul_f32_e32 v65, v65, v74
	v_mul_f32_e32 v74, v98, v75
	v_mul_f32_e32 v74, v66, v74
	v_mul_f32_e32 v66, v99, v72
	v_mul_f32_e32 v75, v67, v66
	v_med3_f32 v67, v68, s63, v154
	v_med3_f32 v68, v69, s63, v154
	v_cvt_pk_fp8_f32 v66, v67, v68
	v_med3_f32 v64, v64, s63, v154
	v_med3_f32 v65, v65, s63, v154
	v_cvt_pk_fp8_f32 v67, v64, v65
	v_med3_f32 v70, v70, s63, v154
	v_med3_f32 v71, v71, s63, v154
; __device__ __forceinline__ u32x4 pack8bf(const f32x4 a, const f32x4 b) { u32x4 w; w.x = cvt_pk_bf16(a[0], a[1]); w.y = cvt_pk_bf16(a[2], a[3]); w.z = cvt_pk_bf16(b[0], b[1]); w.w = cvt_pk_bf16(b[2], b[3]); return w; }
; __device__ __forceinline__ void ln_stats(const float* st, int row, float& mu, float& rs) { const f32x2 s = *(const f32x2*)(st + 2 * (size_t)row); mu = s[0] * (1.0f / DM); rs = 1.0f / sqrtf(s[1] * (1.0f / DM) - mu * mu + LN_EPS); }
;     __device__ __forceinline__ void operator()(EPI_ARGS) const {
;     ...
; #pragma unroll
;         for (int ai = 0; ai < 2; ++ai)
; #pragma unroll
;             for (int m = 0; m < 4; ++m) { const int row = row0 + ai * HALF + m * 16; f32x4 r[2];
;                 float mu = 0.f, rs = 1.f; if constexpr (FOLD) ln_stats(st, row, mu, rs);
; #pragma unroll
;                 for (int n = 0; n < 2; ++n) { f32x4 g = acc[ai][0][m][n], up = acc[ai][1][m][n];
;                     if constexpr (!PRE) { g = g * ascale; up = up * ascale; }
;                     if constexpr (FOLD) { g = (g - cg[n] * mu) * rs + dg[n]; up = (up - cu[n] * mu) * rs + du[n]; }
;                     if constexpr (!PRE) up = up * oscale;
; #pragma unroll
;                     for (int j = 0; j < 4; ++j) { const float e = __builtin_amdgcn_exp2f(g[j] * -1.4426950408889634f); r[n][j] = g[j] * __builtin_amdgcn_rcpf(1.0f + e) * up[j]; } }
;                 if constexpr (F8OUT) *(u32x2*)((unsigned char*)O + (size_t)row * ldc + col0) = pack8fp8(r[0], r[1]);
;                 else *(u32x4*)((bf16_t*)O + (size_t)row * ldc + col0) = pack8bf(r[0], r[1]); }
	v_cvt_pk_fp8_f32 v66, v70, v71 op_sel:[0,0,1]
	v_med3_f32 v64, v74, s63, v154
	v_med3_f32 v65, v75, s63, v154
	v_mul_f32_e32 v70, 0xb7afc6c0, v60
	v_cvt_pk_fp8_f32 v67, v64, v65 op_sel:[0,0,1]
	v_exp_f32_e32 v70, v70
	v_mul_f32_e32 v71, 0xb7afc6c0, v61
	v_or_b32_e32 v72, 48, v156
	v_exp_f32_e32 v71, v71
	v_mad_i64_i32 v[64:65], s[4:5], v72, s64, v[144:145]
	v_lshl_add_u64 v[64:65], v[64:65], 0, v[146:147]
	global_store_dwordx2 v[64:65], v[66:67], off
	v_fma_f32 v66, v70, s32, s32
	v_rcp_f32_e32 v66, v66
	v_fma_f32 v67, v71, s32, s32
	v_rcp_f32_e32 v67, v67
	v_mul_f32_e32 v60, v60, v66
	v_mul_f32_e32 v66, 0xb7afc6c0, v62
	v_mul_f32_e32 v61, v61, v67
	v_exp_f32_e32 v66, v66
	v_mul_f32_e32 v67, 0xb7afc6c0, v63
	v_exp_f32_e32 v67, v67
	v_mul_f32_e32 v65, 0xb7afc6c0, v56
	v_fma_f32 v66, v66, s32, s32
	v_rcp_f32_e32 v66, v66
	v_fma_f32 v67, v67, s32, s32
	v_exp_f32_e32 v65, v65
	v_rcp_f32_e32 v67, v67
	v_mul_f32_e32 v62, v62, v66
	v_mul_f32_e32 v60, v28, v60
	v_fma_f32 v66, v65, s32, s32
	v_mul_f32_e32 v63, v63, v67
	v_rcp_f32_e32 v66, v66
	v_mul_f32_e32 v67, 0xb7afc6c0, v57
	v_exp_f32_e32 v67, v67
	v_mul_f32_e32 v61, v29, v61
	v_mul_f32_e32 v56, v56, v66
	v_mul_f32_e32 v24, v24, v56
	v_fma_f32 v56, v67, s32, s32
	v_mul_f32_e32 v66, 0xb7afc6c0, v58
	v_rcp_f32_e32 v56, v56
	v_exp_f32_e32 v66, v66
	v_mul_f32_e32 v67, 0xb7afc6c0, v59
	v_exp_f32_e32 v67, v67
	v_mul_f32_e32 v56, v57, v56
	v_fma_f32 v57, v66, s32, s32
	v_rcp_f32_e32 v57, v57
	v_fma_f32 v66, v67, s32, s32
	v_rcp_f32_e32 v66, v66
	v_mul_f32_e32 v25, v25, v56
	v_mul_f32_e32 v58, v58, v57
	v_mul_f32_e32 v58, v26, v58
	v_mul_f32_e32 v26, v59, v66
	v_mul_f32_e32 v59, v27, v26
	v_med3_f32 v27, v60, s63, v154
	v_med3_f32 v56, v61, s63, v154
	v_cvt_pk_fp8_f32 v26, v27, v56
	v_med3_f32 v24, v24, s63, v154
	v_med3_f32 v25, v25, s63, v154
	v_cvt_pk_fp8_f32 v27, v24, v25
	v_med3_f32 v24, v58, s63, v154
	v_mul_f32_e32 v58, 0xb7afc6c0, v52
	v_mul_f32_e32 v62, v30, v62
	v_mul_f32_e32 v63, v31, v63
	v_med3_f32 v25, v59, s63, v154
	v_exp_f32_e32 v58, v58
	v_mul_f32_e32 v59, 0xb7afc6c0, v53
	v_med3_f32 v56, v62, s63, v154
	v_med3_f32 v57, v63, s63, v154
	v_exp_f32_e32 v59, v59
	v_cvt_pk_fp8_f32 v26, v56, v57 op_sel:[0,0,1]
	v_cvt_pk_fp8_f32 v27, v24, v25 op_sel:[0,0,1]
	v_add_u32_e32 v64, 0x80, v156
	v_mad_i64_i32 v[24:25], s[4:5], v64, s64, v[144:145]
	v_fma_f32 v58, v58, s32, s32
	v_lshl_add_u64 v[24:25], v[24:25], 0, v[146:147]
	v_rcp_f32_e32 v58, v58
	v_fma_f32 v59, v59, s32, s32
	v_rcp_f32_e32 v59, v59
	global_store_dwordx2 v[24:25], v[26:27], off
	v_mul_f32_e32 v27, 0xb7afc6c0, v54
	v_exp_f32_e32 v27, v27
	v_mul_f32_e32 v24, 0xb7afc6c0, v55
	v_exp_f32_e32 v24, v24
	v_mul_f32_e32 v26, v52, v58
	v_mul_f32_e32 v20, v20, v26
	v_mul_f32_e32 v26, v53, v59
	v_mul_f32_e32 v21, v21, v26
	v_fma_f32 v26, v27, s32, s32
	v_rcp_f32_e32 v26, v26
	v_fma_f32 v27, v24, s32, s32
	v_mul_f32_e32 v24, 0xb7afc6c0, v48
	v_rcp_f32_e32 v27, v27
	v_exp_f32_e32 v24, v24
	v_mul_f32_e32 v26, v54, v26
	v_mul_f32_e32 v22, v22, v26
	v_mul_f32_e32 v26, v55, v27
	v_fma_f32 v27, v24, s32, s32
	v_rcp_f32_e32 v27, v27
	v_mul_f32_e32 v24, 0xb7afc6c0, v49
	v_exp_f32_e32 v24, v24
	v_mul_f32_e32 v23, v23, v26
	v_mul_f32_e32 v26, v48, v27
	v_mul_f32_e32 v27, 0xb7afc6c0, v50
	v_mul_f32_e32 v16, v16, v26
	v_fma_f32 v26, v24, s32, s32
	v_exp_f32_e32 v27, v27
	v_mul_f32_e32 v24, 0xb7afc6c0, v51
	v_exp_f32_e32 v24, v24
	v_rcp_f32_e32 v26, v26
	v_fma_f32 v27, v27, s32, s32
	v_rcp_f32_e32 v27, v27
	v_fma_f32 v24, v24, s32, s32
	v_rcp_f32_e32 v24, v24
	v_mul_f32_e32 v26, v49, v26
	v_mul_f32_e32 v17, v17, v26
	v_mul_f32_e32 v26, v50, v27
	v_mul_f32_e32 v26, v18, v26
	v_mul_f32_e32 v18, v51, v24
	v_mul_f32_e32 v27, v19, v18
	v_med3_f32 v19, v20, s63, v154
	v_med3_f32 v20, v21, s63, v154
	v_cvt_pk_fp8_f32 v18, v19, v20
	v_med3_f32 v16, v16, s63, v154
	v_med3_f32 v17, v17, s63, v154
	v_med3_f32 v22, v22, s63, v154
	v_med3_f32 v23, v23, s63, v154
	v_cvt_pk_fp8_f32 v19, v16, v17
	v_cvt_pk_fp8_f32 v18, v22, v23 op_sel:[0,0,1]
	v_mul_f32_e32 v22, 0xb7afc6c0, v44
	v_exp_f32_e32 v22, v22
	v_mul_f32_e32 v23, 0xb7afc6c0, v45
	v_med3_f32 v16, v26, s63, v154
	v_med3_f32 v17, v27, s63, v154
	v_exp_f32_e32 v23, v23
	v_cvt_pk_fp8_f32 v19, v16, v17 op_sel:[0,0,1]
; __device__ __forceinline__ u32x4 pack8bf(const f32x4 a, const f32x4 b) { u32x4 w; w.x = cvt_pk_bf16(a[0], a[1]); w.y = cvt_pk_bf16(a[2], a[3]); w.z = cvt_pk_bf16(b[0], b[1]); w.w = cvt_pk_bf16(b[2], b[3]); return w; }
;     __device__ __forceinline__ float qscale(const Unit& u) const { return ((u.pn >= 8 && u.pn <= 11) || u.pn == 17) ? 0.5f : 1.0f; }
; __device__ __forceinline__ void ln_stats(const float* st, int row, float& mu, float& rs) { const f32x2 s = *(const f32x2*)(st + 2 * (size_t)row); mu = s[0] * (1.0f / DM); rs = 1.0f / sqrtf(s[1] * (1.0f / DM) - mu * mu + LN_EPS); }
;     ...
;         if constexpr (QM == 2) { const float qs0_ = g.qs * E.qscale(cur), qs1_ = qs0_ * g.qs_b1; _Pragma("unroll") for (int a = 0; a < 2; ++a) _Pragma("unroll") for (int b = 0; b < 2; ++b) _Pragma("unroll") for (int m = 0; m < 4; ++m) _Pragma("unroll") for (int n = 0; n < 2; ++n) { const v4i t_ = __builtin_bit_cast(v4i, acc[a][b][m][n]); acc[a][b][m][n] = (f32x4){(float)t_[0], (float)t_[1], (float)t_[2], (float)t_[3]} * (b == 0 ? qs0_ : qs1_); } }
;     __device__ __forceinline__ void operator()(EPI_ARGS) const {
;     ...
; #pragma unroll
;         for (int ai = 0; ai < 2; ++ai)
; #pragma unroll
;             for (int m = 0; m < 4; ++m) { const int row = row0 + ai * HALF + m * 16; f32x4 r[2];
;                 float mu = 0.f, rs = 1.f; if constexpr (FOLD) ln_stats(st, row, mu, rs);
; #pragma unroll
;                 for (int n = 0; n < 2; ++n) { f32x4 g = acc[ai][0][m][n], up = acc[ai][1][m][n];
;                     if constexpr (!PRE) { g = g * ascale; up = up * ascale; }
;                     if constexpr (FOLD) { g = (g - cg[n] * mu) * rs + dg[n]; up = (up - cu[n] * mu) * rs + du[n]; }
;                     if constexpr (!PRE) up = up * oscale;
; #pragma unroll
;                     for (int j = 0; j < 4; ++j) { const float e = __builtin_amdgcn_exp2f(g[j] * -1.4426950408889634f); r[n][j] = g[j] * __builtin_amdgcn_rcpf(1.0f + e) * up[j]; } }
;                 if constexpr (F8OUT) *(u32x2*)((unsigned char*)O + (size_t)row * ldc + col0) = pack8fp8(r[0], r[1]);
;                 else *(u32x4*)((bf16_t*)O + (size_t)row * ldc + col0) = pack8bf(r[0], r[1]); }
	v_add_u32_e32 v24, 0x90, v156
	v_mad_i64_i32 v[16:17], s[4:5], v24, s64, v[144:145]
	v_fma_f32 v22, v22, s32, s32
	v_lshl_add_u64 v[16:17], v[16:17], 0, v[146:147]
	v_rcp_f32_e32 v22, v22
	v_fma_f32 v23, v23, s32, s32
	v_rcp_f32_e32 v23, v23
	global_store_dwordx2 v[16:17], v[18:19], off
	v_mul_f32_e32 v19, 0xb7afc6c0, v46
	v_exp_f32_e32 v19, v19
	v_mul_f32_e32 v16, 0xb7afc6c0, v47
	v_exp_f32_e32 v16, v16
	v_mul_f32_e32 v18, v44, v22
	v_mul_f32_e32 v12, v12, v18
	v_mul_f32_e32 v18, v45, v23
	v_mul_f32_e32 v13, v13, v18
	v_fma_f32 v18, v19, s32, s32
	v_rcp_f32_e32 v18, v18
	v_fma_f32 v19, v16, s32, s32
	v_mul_f32_e32 v16, 0xb7afc6c0, v40
	v_rcp_f32_e32 v19, v19
	v_exp_f32_e32 v16, v16
	v_mul_f32_e32 v18, v46, v18
	v_mul_f32_e32 v14, v14, v18
	v_mul_f32_e32 v18, v47, v19
	v_fma_f32 v19, v16, s32, s32
	v_rcp_f32_e32 v19, v19
	v_mul_f32_e32 v16, 0xb7afc6c0, v41
	v_exp_f32_e32 v16, v16
	v_mul_f32_e32 v15, v15, v18
	v_mul_f32_e32 v18, v40, v19
	v_mul_f32_e32 v19, 0xb7afc6c0, v42
	v_mul_f32_e32 v8, v8, v18
	v_fma_f32 v18, v16, s32, s32
	v_exp_f32_e32 v19, v19
	v_mul_f32_e32 v16, 0xb7afc6c0, v43
	v_exp_f32_e32 v16, v16
	v_rcp_f32_e32 v18, v18
	v_fma_f32 v19, v19, s32, s32
	v_cvt_f32_i32_e32 v11, v11
	v_cvt_f32_i32_e32 v10, v10
	v_rcp_f32_e32 v19, v19
	v_fma_f32 v16, v16, s32, s32
	v_rcp_f32_e32 v16, v16
	v_mul_f32_e32 v18, v41, v18
	v_mul_f32_e32 v9, v9, v18
	v_mul_f32_e32 v18, v42, v19
	v_mul_f32_e32 v18, v10, v18
	v_mul_f32_e32 v10, v43, v16
	v_mul_f32_e32 v19, v11, v10
	v_med3_f32 v11, v12, s63, v154
	v_med3_f32 v12, v13, s63, v154
	v_cvt_pk_fp8_f32 v10, v11, v12
	v_med3_f32 v8, v8, s63, v154
	v_med3_f32 v9, v9, s63, v154
	v_med3_f32 v14, v14, s63, v154
	v_med3_f32 v15, v15, s63, v154
	v_cvt_pk_fp8_f32 v11, v8, v9
	v_cvt_pk_fp8_f32 v10, v14, v15 op_sel:[0,0,1]
	v_mul_f32_e32 v14, 0xb7afc6c0, v36
	v_exp_f32_e32 v14, v14
	v_mul_f32_e32 v15, 0xb7afc6c0, v37
	v_med3_f32 v8, v18, s63, v154
	v_med3_f32 v9, v19, s63, v154
	v_exp_f32_e32 v15, v15
	v_cvt_pk_fp8_f32 v11, v8, v9 op_sel:[0,0,1]
	v_add_u32_e32 v16, 0xa0, v156
	v_mad_i64_i32 v[8:9], s[4:5], v16, s64, v[144:145]
	v_fma_f32 v14, v14, s32, s32
	v_lshl_add_u64 v[8:9], v[8:9], 0, v[146:147]
	v_rcp_f32_e32 v14, v14
	v_fma_f32 v15, v15, s32, s32
	v_rcp_f32_e32 v15, v15
	global_store_dwordx2 v[8:9], v[10:11], off
	v_mul_f32_e32 v11, 0xb7afc6c0, v38
	v_exp_f32_e32 v11, v11
	v_mul_f32_e32 v8, 0xb7afc6c0, v39
	v_exp_f32_e32 v8, v8
	v_mul_f32_e32 v10, v36, v14
	v_mul_f32_e32 v4, v4, v10
	v_mul_f32_e32 v10, v37, v15
	v_mul_f32_e32 v5, v5, v10
	v_fma_f32 v10, v11, s32, s32
	v_cvt_f32_i32_e32 v7, v7
	v_cvt_f32_i32_e32 v6, v6
	v_rcp_f32_e32 v10, v10
	v_fma_f32 v11, v8, s32, s32
	v_mul_f32_e32 v8, 0xb7afc6c0, v32
	v_rcp_f32_e32 v11, v11
	v_exp_f32_e32 v8, v8
	v_mul_f32_e32 v10, v38, v10
	v_mul_f32_e32 v6, v6, v10
	v_mul_f32_e32 v10, v39, v11
	v_fma_f32 v11, v8, s32, s32
	v_rcp_f32_e32 v11, v11
	v_mul_f32_e32 v8, 0xb7afc6c0, v33
	v_exp_f32_e32 v8, v8
	v_mul_f32_e32 v7, v7, v10
	v_mul_f32_e32 v10, v32, v11
	v_mul_f32_e32 v11, 0xb7afc6c0, v34
	v_mul_f32_e32 v0, v0, v10
	v_fma_f32 v10, v8, s32, s32
	v_exp_f32_e32 v11, v11
	v_mul_f32_e32 v8, 0xb7afc6c0, v35
	v_exp_f32_e32 v8, v8
	v_rcp_f32_e32 v10, v10
	v_fma_f32 v11, v11, s32, s32
	v_cvt_f32_i32_e32 v3, v3
	v_cvt_f32_i32_e32 v2, v2
	v_rcp_f32_e32 v11, v11
	v_fma_f32 v8, v8, s32, s32
	v_rcp_f32_e32 v8, v8
	v_mul_f32_e32 v10, v33, v10
	v_mul_f32_e32 v1, v1, v10
	v_mul_f32_e32 v10, v34, v11
	v_mul_f32_e32 v10, v2, v10
	v_mul_f32_e32 v2, v35, v8
	v_mul_f32_e32 v11, v3, v2
	v_med3_f32 v3, v4, s63, v154
	v_med3_f32 v4, v5, s63, v154
	v_cvt_pk_fp8_f32 v2, v3, v4
	v_med3_f32 v0, v0, s63, v154
	v_med3_f32 v1, v1, s63, v154
	v_cvt_pk_fp8_f32 v3, v0, v1
	v_med3_f32 v6, v6, s63, v154
	v_med3_f32 v7, v7, s63, v154
	v_med3_f32 v0, v10, s63, v154
	v_med3_f32 v1, v11, s63, v154
	v_cvt_pk_fp8_f32 v2, v6, v7 op_sel:[0,0,1]
	v_cvt_pk_fp8_f32 v3, v0, v1 op_sel:[0,0,1]
	v_add_u32_e32 v8, 0xb0, v156
	v_mad_i64_i32 v[0:1], s[4:5], v8, s64, v[144:145]
	v_lshl_add_u64 v[0:1], v[0:1], 0, v[146:147]
	s_and_b64 vcc, exec, s[2:3]
	s_mov_b64 s[2:3], -1
	global_store_dwordx2 v[0:1], v[2:3], off
	s_cbranch_vccnz .LBB0_4732
	s_andn2_b64 vcc, exec, s[14:15]
	s_cbranch_vccnz .LBB0_4731
	s_barrier
	s_branch .LBB0_4731
